# retention: next chunk K/V/Q global loads issued at the loop bottom before the chunk-top barrier, on top of v6
# speedup vs baseline: 1.0080x; 1.0080x over previous
; #define LAS __attribute__((address_space(3)))
; __device__ __forceinline__ void retention_fused(const Params& p, LAS unsigned char* lds, int unit) {
;     const int tid = threadIdx.x, lane = tid & 63, wid = __builtin_amdgcn_readfirstlane(tid >> 6), fr = lane & 15, fq = lane >> 4;
;     const int b = unit >> 5, h = (unit >> 3) & 3, vb = unit & 7;
;     unsigned char* ws = p.ws;
;     const bf16_t* Qg = (const bf16_t*)(ws + WS_Q) + (size_t)b * SEQ * D + h * 256;
;     const bf16_t* Kg = (const bf16_t*)(ws + WS_K) + (size_t)b * SEQ * D + h * 256;
;     const bf16_t* Vg = (const bf16_t*)(ws + WS_V) + (size_t)b * SEQ * VD + h * 512 + vb * 64;
;     bf16_t* Og = (bf16_t*)(ws + WS_O) + (size_t)b * SEQ * VD + h * 512 + vb * 64;
;     const float log2g = __log2f(1.0f - exp2f(-5.0f - (float)h));
;     const float gC = exp2f(128.0f * log2g);
;     f32x4 S[2][4];
; #pragma unroll
;     for (int mt = 0; mt < 2; ++mt)
; #pragma unroll
;         for (int nt = 0; nt < 4; ++nt) S[mt][nt] = (f32x4){0.f, 0.f, 0.f, 0.f};
;     LAS unsigned char* Ks = lds + LDS_KS; LAS unsigned char* Vs = lds + LDS_VS; LAS unsigned char* Vw = lds + LDS_VW; LAS unsigned char* St = lds + LDS_ST;
;     LAS f32x4* qs = (LAS f32x4*)(lds + LDS_FQ); LAS f32x4* kws = (LAS f32x4*)(lds + LDS_FK); LAS float* asc = (LAS float*)(lds + LDS_FA); LAS float* red = (LAS float*)(lds + 0);
;     const int v4 = tid & 127, rg = tid >> 7;
;     u32x2 vjp[4]; f32x4 oa[4];
;     const float* S0 = nullptr; float* S1 = nullptr; bf16_t* Ogs = nullptr;
;     float sg = 0.f, sg2 = 0.f, sg3 = 0.f, sg4 = 0.f;
; #pragma unroll
;     for (int i = 0; i < 4; ++i) { vjp[i] = (u32x2){0u, 0u}; oa[i] = (f32x4){0.f, 0.f, 0.f, 0.f}; }
.LBB0_1034:
	s_and_b64 vcc, exec, s[0:1]
	s_cbranch_vccz .LBB0_1059
	v_and_b32_e32 v248, 0x100, v146
	v_lshrrev_b32_e32 v249, 1, v248
	v_lshrrev_b32_e32 v248, 2, v248
	v_or_b32_e32 v248, v248, v249
	v_xor_b32_e32 v146, v146, v248
	s_ashr_i32 s16, s78, 5
	s_bfe_u32 s33, s78, 0x20003
	s_ashr_i32 s17, s16, 31
	s_add_u32 s10, s74, 0xc009000
	s_addc_u32 s11, s75, 0
	s_lshl_b64 s[0:1], s[16:17], 22
	s_add_u32 s2, s10, s0
	s_addc_u32 s3, s11, s1
	s_lshl_b32 s8, s33, 9
	s_add_u32 s2, s2, s8
	s_addc_u32 s3, s3, 0
	s_lshl_b32 s4, s78, 6
	s_and_b32 s36, s4, 0x1c0
	s_add_u32 s12, s74, 0x16509000
	s_addc_u32 s13, s75, 0
	s_lshl_b64 s[4:5], s[16:17], 23
	v_cvt_f32_ubyte0_e32 v1, s33
	s_add_u32 s6, s12, s4
	v_sub_f32_e32 v1, 0xc0a00000, v1
	s_mov_b32 s15, 0xc2fc0000
	s_addc_u32 s7, s13, s5
	s_lshl_b32 s9, s33, 10
	v_mov_b32_e32 v4, 0x42800000
	v_cmp_gt_f32_e32 vcc, s15, v1
	s_add_u32 s14, s6, s9
	s_addc_u32 s18, s7, 0
	v_cndmask_b32_e32 v2, 0, v4, vcc
	v_add_f32_e32 v1, v1, v2
	v_exp_f32_e32 v1, v1
	s_and_b64 s[6:7], vcc, exec
	v_readfirstlane_b32 s22, v146
	s_cselect_b32 s6, 0xffffffc0, 0
	s_lshr_b32 s17, s22, 6
	s_add_u32 s20, s74, 0x9f09000
	s_addc_u32 s21, s75, 0
	v_ldexp_f32 v1, v1, s6
	s_add_u32 s6, s20, s0
	s_addc_u32 s7, s21, s1
	s_add_u32 s23, s74, 0xe109000
	v_sub_f32_e32 v1, 1.0, v1
	s_addc_u32 s24, s75, 0
	v_log_f32_e32 v153, v1
	s_add_u32 s0, s23, s4
	s_addc_u32 s1, s24, s5
	s_add_u32 s9, s0, s9
	s_addc_u32 s25, s1, 0
	s_lshl_b32 s26, s36, 1
	v_mul_f32_e32 v1, 0x43000000, v153
	s_add_u32 s0, s14, s26
	s_addc_u32 s1, s18, 0
	v_cmp_gt_f32_e32 vcc, s15, v1
	s_add_u32 s4, s6, s8
	s_addc_u32 s5, s7, 0
	v_cndmask_b32_e32 v1, 0, v4, vcc
	v_fmac_f32_e32 v1, 0x43000000, v153
	s_add_u32 s6, s9, s26
	v_exp_f32_e32 v1, v1
	s_addc_u32 s7, s25, 0
	v_and_b32_e32 v2, 31, v146
	s_and_b64 s[8:9], vcc, exec
	v_lshlrev_b32_e32 v118, 4, v2
	v_mov_b32_e32 v119, 0
	v_and_b32_e32 v2, 7, v146
	v_and_b32_e32 v114, 15, v146
	s_cselect_b32 s8, 0xffffffc0, 0
	v_lshl_add_u64 v[120:121], s[2:3], 0, v[118:119]
	v_add_u32_e32 v15, 0, v118
	v_lshlrev_b32_e32 v118, 4, v2
	v_lshlrev_b32_e32 v2, 3, v146
	v_ldexp_f32 v116, v1, s8
	s_and_b32 s8, s22, 0xffffffc0
	v_and_b32_e32 v18, 24, v2
	v_lshlrev_b32_e32 v2, 1, v114
	v_mov_b32_e32 v3, v119
	v_lshl_add_u64 v[126:127], s[0:1], 0, v[2:3]
	s_add_i32 s0, s8, 0
	s_add_i32 s9, 0, 0x19000
	s_add_i32 s2, 0, 0x10800
	v_add_u32_e32 v19, s0, v18
	s_and_b32 s0, s78, 3
	v_bfe_u32 v9, v146, 4, 2
	s_add_i32 s18, s9, s8
	v_add_u32_e32 v184, s2, v118
	s_add_i32 s2, 0, 0x14c00
	s_lshl_b32 s37, s17, 4
	s_lshl_b32 s1, s0, 9
	v_lshlrev_b32_e32 v1, 3, v9
	v_bfe_u32 v17, v146, 2, 2
	s_add_u32 s38, s20, s1
	v_add_u32_e32 v14, s18, v1
	v_or_b32_e32 v3, v1, v17
	s_addc_u32 s39, s21, 0
	v_cvt_f32_ubyte0_e32 v1, s0
	s_add_u32 s40, s10, s1
	v_sub_f32_e32 v1, 0xc0a00000, v1
	v_lshl_add_u64 v[122:123], s[6:7], 0, v[118:119]
	v_add_u32_e32 v185, s2, v118
	v_and_b32_e32 v118, 48, v146
	s_addc_u32 s41, s11, 0
	s_lshl_b32 s1, s0, 10
	v_cmp_gt_f32_e32 vcc, s15, v1
	v_lshl_add_u64 v[124:125], s[4:5], 0, v[118:119]
	s_add_u32 s4, s23, s1
	v_cndmask_b32_e32 v2, 0, v4, vcc
	s_addc_u32 s5, s24, 0
	v_add_f32_e32 v1, v1, v2
	s_add_u32 s42, s12, s1
	v_exp_f32_e32 v1, v1
	s_addc_u32 s43, s13, 0
	s_and_b64 s[0:1], vcc, exec
	s_cselect_b32 s0, 0xffffffc0, 0
	v_ldexp_f32 v1, v1, s0
	v_and_b32_e32 v5, 0x7f, v146
	v_sub_f32_e32 v131, 1.0, v1
	v_lshlrev_b32_e32 v1, 4, v146
	s_add_i32 s44, 0, 0x21400
	s_add_i32 s45, 0, 0x22400
	v_add_u32_e32 v187, s44, v1
	v_add_u32_e32 v188, s45, v1
	v_lshlrev_b32_e32 v10, 3, v5
	v_mov_b32_e32 v11, v119
	v_lshrrev_b32_e32 v1, 5, v146
	v_lshl_add_u64 v[136:137], s[4:5], 0, v[10:11]
	v_lshlrev_b32_e32 v191, 10, v1
	v_mul_u32_u24_e32 v11, 0x210, v1
	v_add_u32_e32 v1, 0x200, v146
	v_lshrrev_b32_e32 v12, 5, v1
	v_lshlrev_b32_e32 v192, 10, v12
	v_mul_u32_u24_e32 v21, 0x210, v12
	v_add_u32_e32 v12, 0x600, v146
	v_lshrrev_b32_e32 v12, 5, v12
	v_lshlrev_b32_e32 v194, 10, v12
	v_mul_u32_u24_e32 v22, 0x210, v12
	v_add_u32_e32 v12, 0xa00, v146
	v_lshrrev_b32_e32 v12, 5, v12
	v_lshlrev_b32_e32 v196, 10, v12
	v_mul_u32_u24_e32 v23, 0x210, v12
	v_add_u32_e32 v12, 0xe00, v146
	v_lshrrev_b32_e32 v12, 5, v12
	v_mul_f32_e32 v133, v131, v131
	v_lshlrev_b32_e32 v198, 10, v12
	v_mul_u32_u24_e32 v24, 0x210, v12
	v_lshrrev_b32_e32 v12, 3, v146
	v_lshrrev_b32_e32 v1, 3, v1
	v_mov_b32_e32 v2, v133
	v_mov_b32_e32 v130, v133
	v_lshlrev_b32_e32 v199, 11, v12
	v_mul_u32_u24_e32 v200, 0x88, v12
	v_xor_b32_e32 v12, 0x7f, v12
	v_sub_u32_e32 v13, 0x7f, v1
	v_pk_mul_f32 v[134:135], v[2:3], v[130:131] op_sel_hi:[0,1]
	v_cvt_f32_ubyte0_e32 v12, v12
	v_cvt_f32_i32_e32 v13, v13
	v_lshlrev_b32_e32 v130, 2, v9
	v_mul_f32_e32 v12, v153, v12
	v_or_b32_e32 v203, s37, v130
	v_exp_f32_e32 v140, v12
	v_or_b32_e32 v12, 1, v203
	v_cvt_f32_u32_e32 v12, v12
	v_lshlrev_b32_e32 v201, 11, v1
	v_mul_u32_u24_e32 v202, 0x88, v1
	v_mul_f32_e32 v1, v153, v13
	v_or_b32_e32 v13, 2, v203
	v_cvt_f32_u32_e32 v13, v13
	v_exp_f32_e32 v142, v1
	v_mul_f32_e32 v1, v153, v12
	v_or_b32_e32 v12, 3, v203
	v_cvt_f32_u32_e32 v12, v12
	v_exp_f32_e32 v144, v1
	v_mul_f32_e32 v1, v153, v13
	v_add_u32_e32 v13, 4, v203
	v_cvt_f32_u32_e32 v13, v13
	v_exp_f32_e32 v145, v1
	v_mul_f32_e32 v1, v153, v12
	v_exp_f32_e32 v148, v1
	v_sub_u32_e32 v1, v114, v130
	v_mul_f32_e32 v12, v153, v13
	v_cvt_f32_i32_e32 v13, v1
	v_or_b32_e32 v1, 1, v130
	v_sub_u32_e32 v25, v114, v1
	v_cvt_f32_i32_e32 v25, v25
	v_or_b32_e32 v152, 2, v130
	s_waitcnt lgkmcnt(0)
; #define LAS __attribute__((address_space(3)))
; __device__ __forceinline__ void retention_fused(const Params& p, LAS unsigned char* lds, int unit) {
;     ...
;     const float log2g = __log2f(1.0f - exp2f(-5.0f - (float)h));
;     const float gC = exp2f(128.0f * log2g);
;     f32x4 S[2][4];
; #pragma unroll
;     for (int mt = 0; mt < 2; ++mt)
; #pragma unroll
;         for (int nt = 0; nt < 4; ++nt) S[mt][nt] = (f32x4){0.f, 0.f, 0.f, 0.f};
;     LAS unsigned char* Ks = lds + LDS_KS; LAS unsigned char* Vs = lds + LDS_VS; LAS unsigned char* Vw = lds + LDS_VW; LAS unsigned char* St = lds + LDS_ST;
;     LAS f32x4* qs = (LAS f32x4*)(lds + LDS_FQ); LAS f32x4* kws = (LAS f32x4*)(lds + LDS_FK); LAS float* asc = (LAS float*)(lds + LDS_FA); LAS float* red = (LAS float*)(lds + 0);
;     const int v4 = tid & 127, rg = tid >> 7;
;     u32x2 vjp[4]; f32x4 oa[4];
;     const float* S0 = nullptr; float* S1 = nullptr; bf16_t* Ogs = nullptr;
;     float sg = 0.f, sg2 = 0.f, sg3 = 0.f, sg4 = 0.f;
; #pragma unroll
;     for (int i = 0; i < 4; ++i) { vjp[i] = (u32x2){0u, 0u}; oa[i] = (f32x4){0.f, 0.f, 0.f, 0.f}; }
	v_exp_f32_e32 v149, v12
	v_mul_f32_e32 v12, v153, v13
	v_or_b32_e32 v115, 3, v130
	v_sub_u32_e32 v13, v114, v152
	v_exp_f32_e32 v150, v12
	v_mul_f32_e32 v12, v153, v25
	v_cvt_f32_i32_e32 v13, v13
	v_sub_u32_e32 v25, v114, v115
	v_cvt_f32_i32_e32 v25, v25
	s_lshr_b32 s23, s22, 5
	s_lshr_b32 s18, s22, 7
	s_lshl_b32 s22, s22, 5
	s_and_b32 s26, s22, 0x800
	s_add_i32 s46, 0, 0x23400
	s_lshl_b32 s22, s17, 3
	v_exp_f32_e32 v151, v12
	v_mul_f32_e32 v12, v153, v13
	s_add_i32 s47, s46, s22
	s_or_b32 s22, s23, 1
	v_exp_f32_e32 v154, v12
	v_mul_f32_e32 v12, v153, v25
	v_lshrrev_b32_e32 v183, 7, v146
	v_lshlrev_b32_e32 v138, 4, v5
	s_lshl_b32 s23, s22, 10
	s_lshl_b32 s22, s22, 2
	v_exp_f32_e32 v155, v12
	v_mov_b32_e32 v139, v119
	s_mov_b32 s19, 0
	s_movk_i32 s14, 0x7f
	v_and_b32_e32 v7, 63, v146
	v_or_b32_e32 v2, 0x800, v146
	v_lshl_add_u32 v189, v183, 13, 0
	s_movk_i32 s4, 0xe800
	s_and_b32 s27, s23, 0xc00
	s_add_i32 s48, s46, s22
	v_readlane_b32 s52, v247, 0
	v_lshl_add_u64 v[12:13], s[72:73], 0, v[138:139]
	s_mov_b64 s[22:23], 0x5310000
	v_add_u32_e32 v16, s9, v118
	v_add_u32_e32 v20, s2, v18
	s_movk_i32 s0, 0x100
	v_or_b32_e32 v4, 0xc00, v146
	s_lshl_b64 s[20:21], s[18:19], 11
	v_lshlrev_b32_e32 v6, 2, v7
	v_cmp_eq_u32_e64 s[2:3], 0, v7
	v_lshlrev_b32_e32 v8, 2, v5
	v_lshlrev_b32_e32 v10, 11, v183
	v_mad_i32_i24 v5, v183, s4, v189
	s_movk_i32 s4, 0x80
	v_cmp_lt_u32_e64 s[6:7], s14, v146
	s_movk_i32 s12, 0xff
	s_movk_i32 s14, 0x17f
	s_movk_i32 s24, 0x210
	v_mul_u32_u24_e32 v7, 0x210, v114
	v_mul_u32_u24_e32 v25, 0x210, v3
	v_mul_u32_u24_e32 v3, 0x88, v3
	v_readlane_b32 s53, v247, 1
	v_readlane_b32 s54, v247, 2
	v_readlane_b32 s55, v247, 3
	v_readlane_b32 s56, v247, 4
	v_readlane_b32 s57, v247, 5
	v_readlane_b32 s58, v247, 6
	v_readlane_b32 s59, v247, 7
	v_lshl_add_u64 v[158:159], v[12:13], 0, s[22:23]
	s_lshl_b32 s50, s18, 1
	v_mul_u32_u24_e32 v9, 0x220, v9
	v_mul_u32_u24_e32 v12, 0x88, v17
	s_mov_b32 s18, s19
	v_lshlrev_b32_e32 v206, 1, v2
	v_mbcnt_lo_u32_b32 v2, -1, 0
	v_or_b32_e32 v186, s37, v114
	v_mov_b32_e32 v128, v116
	v_mov_b32_e32 v129, v116
	v_cmp_gt_u32_e64 s[0:1], s0, v146
	v_cmp_gt_u32_e64 s[4:5], s4, v146
	v_cmp_eq_u32_e64 s[8:9], 1, v183
	v_cmp_eq_u32_e64 s[10:11], 2, v183
	v_lshlrev_b32_e32 v190, 4, v183
	v_cmp_lt_u32_e64 s[12:13], s12, v146
	v_cmp_lt_u32_e64 s[14:15], s14, v146
	s_mov_b32 s49, 0x8000
	v_or_b32_e32 v193, 0x8000, v191
	v_or_b32_e32 v195, 0x10000, v191
	v_or_b32_e32 v197, 0x18000, v191
	v_lshl_add_u64 v[156:157], s[58:59], 0, v[138:139]
	v_mov_b32_e32 v141, v140
	v_mov_b32_e32 v143, v142
	v_mov_b32_e32 v132, v135
	v_mad_u32_u24 v139, v114, s24, v118
	s_add_i32 s50, s50, 2
	v_add3_u32 v204, v9, v12, v18
	v_mov_b64_e32 v[164:165], 0
	s_mov_b64 s[24:25], 0
	v_mov_b64_e32 v[168:169], s[18:19]
	s_movk_i32 s51, 0x4000
	v_lshlrev_b32_e32 v205, 1, v146
	v_lshlrev_b32_e32 v207, 1, v4
	v_lshlrev_b32_e32 v118, 1, v6
	s_lshl_b32 s18, s26, 1
	s_lshl_b32 s22, s27, 1
	s_movk_i32 s52, 0x2000
	v_add_u32_e32 v208, v14, v7
	v_add_u32_e32 v209, v15, v11
	v_add_u32_e32 v210, v15, v21
	v_add_u32_e32 v211, v15, v22
	v_add_u32_e32 v212, v15, v23
	v_add_u32_e32 v213, v15, v24
	s_movk_i32 s53, 0x6000
	v_add_u32_e32 v214, v16, v7
	s_mov_b32 s54, 0xa000
	s_mov_b32 s55, 0xc000
	s_mov_b32 s56, 0xe000
	v_add_u32_e32 v215, v19, v25
	v_add_u32_e32 v216, v20, v3
	v_add_u32_e32 v217, v5, v138
	v_lshlrev_b32_e32 v160, 1, v10
	v_lshlrev_b32_e32 v162, 1, v8
	v_mbcnt_hi_u32_b32 v218, -1, v2
	v_mov_b64_e32 v[166:167], 0
	v_mov_b32_e32 v219, v119
	v_mov_b32_e32 v220, v119
	s_mov_b32 s57, s19
	v_mov_b32_e32 v30, v119
	v_mov_b32_e32 v31, v119
	v_mov_b32_e32 v32, v119
	v_mov_b32_e32 v33, v119
	v_mov_b32_e32 v18, v119
	v_mov_b32_e32 v19, v119
	v_mov_b32_e32 v20, v119
	v_mov_b32_e32 v21, v119
; __device__ __forceinline__ unsigned cvt_pk_bf16(float lo, float hi) { const bf16x2_cv v = __builtin_convertvector((f32x2_cv){lo, hi}, bf16x2_cv); return __builtin_bit_cast(unsigned, v); }
; #define LAS __attribute__((address_space(3)))
; __device__ __forceinline__ void retention_fused(const Params& p, LAS unsigned char* lds, int unit) {
;     ...
;     f32x4 S[2][4];
; #pragma unroll
;     for (int mt = 0; mt < 2; ++mt)
; #pragma unroll
;         for (int nt = 0; nt < 4; ++nt) S[mt][nt] = (f32x4){0.f, 0.f, 0.f, 0.f};
;     LAS unsigned char* Ks = lds + LDS_KS; LAS unsigned char* Vs = lds + LDS_VS; LAS unsigned char* Vw = lds + LDS_VW; LAS unsigned char* St = lds + LDS_ST;
;     LAS f32x4* qs = (LAS f32x4*)(lds + LDS_FQ); LAS f32x4* kws = (LAS f32x4*)(lds + LDS_FK); LAS float* asc = (LAS float*)(lds + LDS_FA); LAS float* red = (LAS float*)(lds + 0);
;     const int v4 = tid & 127, rg = tid >> 7;
;     u32x2 vjp[4]; f32x4 oa[4];
;     const float* S0 = nullptr; float* S1 = nullptr; bf16_t* Ogs = nullptr;
;     float sg = 0.f, sg2 = 0.f, sg3 = 0.f, sg4 = 0.f;
; #pragma unroll
;     for (int i = 0; i < 4; ++i) { vjp[i] = (u32x2){0u, 0u}; oa[i] = (f32x4){0.f, 0.f, 0.f, 0.f}; }
;     ...
;         for (int i = 0; i < 8; ++i) { const int id = tid + i * NTHREADS, row = id >> 5, cc = id & 31; *(LAS u32x4*)(Ks + row * KS_STRIDE + cc * 16) = *(const u32x4*)(Kg + (size_t)(c * 128 + row) * D + cc * 8); }
; #pragma unroll
;         for (int i = 0; i < 2; ++i) { const int id = tid + i * NTHREADS, row = id >> 3, cc = id & 7;
;             const u32x4 v = *(const u32x4*)(Vg + (size_t)(c * 128 + row) * VD + cc * 8);
;             *(LAS u32x4*)(Vs + row * VS_STRIDE + cc * 16) = v;
;             const float sw = __builtin_amdgcn_exp2f((float)(127 - row) * log2g);
;             u32x4 w; w.x = cvt_pk_bf16(bflo(v.x) * sw, bfhi(v.x) * sw); w.y = cvt_pk_bf16(bflo(v.y) * sw, bfhi(v.y) * sw); w.z = cvt_pk_bf16(bflo(v.z) * sw, bfhi(v.z) * sw); w.w = cvt_pk_bf16(bflo(v.w) * sw, bfhi(v.w) * sw);
;             *(LAS u32x4*)(Vw + row * VS_STRIDE + cc * 16) = w; }
;         bf16x8 qf[8];
; #pragma unroll
;         for (int ks = 0; ks < 8; ++ks) qf[ks] = *(const bf16x8*)(Qg + (size_t)(c * 128 + 16 * wid + fr) * D + ks * 32 + fq * 8);
	v_mov_b32_e32 v22, v119
	v_mov_b32_e32 v23, v119
	v_mov_b32_e32 v24, v119
	v_mov_b32_e32 v25, v119
	v_mov_b32_e32 v26, v119
	v_mov_b32_e32 v27, v119
	v_mov_b32_e32 v28, v119
	v_mov_b32_e32 v29, v119
	v_mov_b32_e32 v2, v119
	v_mov_b32_e32 v3, v119
	v_mov_b32_e32 v4, v119
	v_mov_b32_e32 v5, v119
	v_mov_b32_e32 v6, v119
	v_mov_b32_e32 v7, v119
	v_mov_b32_e32 v8, v119
	v_mov_b32_e32 v9, v119
	v_mov_b32_e32 v10, v119
	v_mov_b32_e32 v11, v119
	v_mov_b32_e32 v12, v119
	v_mov_b32_e32 v13, v119
	v_mov_b32_e32 v14, v119
	v_mov_b32_e32 v15, v119
	v_mov_b32_e32 v16, v119
	v_mov_b32_e32 v17, v119
	v_mov_b32_e32 v34, v119
	v_mov_b32_e32 v35, v119
	v_mov_b32_e32 v36, v119
	v_mov_b32_e32 v37, v119
	v_mov_b32_e32 v38, v119
	v_mov_b32_e32 v39, v119
	v_mov_b32_e32 v40, v119
	v_mov_b32_e32 v41, v119
	v_mov_b32_e32 v42, v119
	v_mov_b32_e32 v43, v119
	v_mov_b32_e32 v44, v119
	v_mov_b32_e32 v45, v119
	v_mov_b32_e32 v46, v119
	v_mov_b32_e32 v47, v119
	v_mov_b32_e32 v48, v119
	v_mov_b32_e32 v49, v119
	v_mov_b32_e32 v170, v119
	v_mov_b32_e32 v171, v119
	v_mov_b32_e32 v172, v119
	v_mov_b32_e32 v173, v119
	v_mov_b32_e32 v174, v119
	v_mov_b32_e32 v175, v119
	v_mov_b32_e32 v176, v119
	v_mov_b32_e32 v177, v119
	v_readlane_b32 s60, v247, 8
	v_readlane_b32 s61, v247, 9
	v_readlane_b32 s62, v247, 10
	v_readlane_b32 s63, v247, 11
	v_readlane_b32 s64, v247, 12
	v_readlane_b32 s65, v247, 13
	v_readlane_b32 s66, v247, 14
	v_readlane_b32 s67, v247, 15
	s_lshl_b32 s23, s57, 17
	v_or_b32_e32 v50, s23, v191
	v_or_b32_e32 v52, s23, v192
	v_or_b32_e32 v58, s23, v193
	v_or_b32_e32 v60, s23, v194
	v_lshlrev_b32_e32 v50, 1, v50
	v_mov_b32_e32 v51, v119
	v_lshlrev_b32_e32 v52, 1, v52
	v_mov_b32_e32 v53, v119
	v_lshlrev_b32_e32 v58, 1, v58
	v_mov_b32_e32 v59, v119
	v_lshlrev_b32_e32 v60, 1, v60
	v_mov_b32_e32 v61, v119
	v_lshl_add_u64 v[50:51], v[120:121], 0, v[50:51]
	v_lshl_add_u64 v[54:55], v[120:121], 0, v[52:53]
	v_lshl_add_u64 v[58:59], v[120:121], 0, v[58:59]
	v_lshl_add_u64 v[62:63], v[120:121], 0, v[60:61]
	global_load_dwordx4 v[50:53], v[50:51], off
	s_nop 0
	global_load_dwordx4 v[54:57], v[54:55], off
	s_nop 0
	global_load_dwordx4 v[58:61], v[58:59], off
	s_nop 0
	global_load_dwordx4 v[62:65], v[62:63], off
	v_or_b32_e32 v66, s23, v195
	v_or_b32_e32 v68, s23, v196
	v_lshlrev_b32_e32 v66, 1, v66
	v_mov_b32_e32 v67, v119
	v_lshlrev_b32_e32 v68, 1, v68
	v_mov_b32_e32 v69, v119
	v_or_b32_e32 v74, s23, v197
	v_lshl_add_u64 v[66:67], v[120:121], 0, v[66:67]
	v_lshl_add_u64 v[70:71], v[120:121], 0, v[68:69]
	v_lshlrev_b32_e32 v74, 1, v74
	v_mov_b32_e32 v75, v119
	v_add_lshl_u32 v76, s23, v198, 1
	v_mov_b32_e32 v77, v119
	global_load_dwordx4 v[66:69], v[66:67], off
	s_nop 0
	global_load_dwordx4 v[70:73], v[70:71], off
	v_lshl_add_u64 v[74:75], v[120:121], 0, v[74:75]
	v_lshl_add_u64 v[78:79], v[120:121], 0, v[76:77]
	global_load_dwordx4 v[74:77], v[74:75], off
	s_nop 0
	global_load_dwordx4 v[78:81], v[78:79], off
	s_lshl_b32 s23, s57, 18
	v_or_b32_e32 v82, s23, v199
	v_lshlrev_b32_e32 v82, 1, v82
	v_mov_b32_e32 v83, v119
	v_lshl_add_u64 v[82:83], v[122:123], 0, v[82:83]
	global_load_dwordx4 v[178:181], v[82:83], off
	v_add_lshl_u32 v82, s23, v201, 1
	v_mov_b32_e32 v83, v119
	v_lshl_add_u64 v[82:83], v[122:123], 0, v[82:83]
	global_load_dwordx4 v[222:225], v[82:83], off
	s_lshl_b32 s23, s57, 7
	v_mov_b32_e32 v83, v119
	v_add_u32_e32 v82, s23, v186
	v_lshlrev_b64 v[82:83], 11, v[82:83]
	v_lshl_add_u64 v[110:111], v[124:125], 0, v[82:83]
	global_load_dwordx4 v[82:85], v[110:111], off
	global_load_dwordx4 v[86:89], v[110:111], off offset:64
	global_load_dwordx4 v[90:93], v[110:111], off offset:128
	global_load_dwordx4 v[94:97], v[110:111], off offset:192
	global_load_dwordx4 v[98:101], v[110:111], off offset:256
	s_branch .LBB0_1038

; __device__ __forceinline__ unsigned cvt_pk_bf16(float lo, float hi) { const bf16x2_cv v = __builtin_convertvector((f32x2_cv){lo, hi}, bf16x2_cv); return __builtin_bit_cast(unsigned, v); }
; #define LAS __attribute__((address_space(3)))
; __device__ __forceinline__ void retention_fused(const Params& p, LAS unsigned char* lds, int unit) {
;     ...
;     for (int c = 0; c < 16; ++c) {
;     ...
;         for (int i = 0; i < 8; ++i) { const int id = tid + i * NTHREADS, row = id >> 5, cc = id & 31; *(LAS u32x4*)(Ks + row * KS_STRIDE + cc * 16) = *(const u32x4*)(Kg + (size_t)(c * 128 + row) * D + cc * 8); }
; #pragma unroll
;         for (int i = 0; i < 2; ++i) { const int id = tid + i * NTHREADS, row = id >> 3, cc = id & 7;
;             const u32x4 v = *(const u32x4*)(Vg + (size_t)(c * 128 + row) * VD + cc * 8);
;             *(LAS u32x4*)(Vs + row * VS_STRIDE + cc * 16) = v;
;             const float sw = __builtin_amdgcn_exp2f((float)(127 - row) * log2g);
;             u32x4 w; w.x = cvt_pk_bf16(bflo(v.x) * sw, bfhi(v.x) * sw); w.y = cvt_pk_bf16(bflo(v.y) * sw, bfhi(v.y) * sw); w.z = cvt_pk_bf16(bflo(v.z) * sw, bfhi(v.z) * sw); w.w = cvt_pk_bf16(bflo(v.w) * sw, bfhi(v.w) * sw);
;             *(LAS u32x4*)(Vw + row * VS_STRIDE + cc * 16) = w; }
;         bf16x8 qf[8];
; #pragma unroll
;         for (int ks = 0; ks < 8; ++ks) qf[ks] = *(const bf16x8*)(Qg + (size_t)(c * 128 + 16 * wid + fr) * D + ks * 32 + fq * 8);
.LBB0_1037:
	s_add_i32 s57, s57, 1
	s_cmp_lg_u32 s57, 16
	s_cbranch_scc0 .LBB0_1058
	s_lshl_b32 s23, s57, 17
	v_or_b32_e32 v50, s23, v191
	v_or_b32_e32 v52, s23, v192
	v_or_b32_e32 v58, s23, v193
	v_or_b32_e32 v60, s23, v194
	v_lshlrev_b32_e32 v50, 1, v50
	v_mov_b32_e32 v51, v119
	v_lshlrev_b32_e32 v52, 1, v52
	v_mov_b32_e32 v53, v119
	v_lshlrev_b32_e32 v58, 1, v58
	v_mov_b32_e32 v59, v119
	v_lshlrev_b32_e32 v60, 1, v60
	v_mov_b32_e32 v61, v119
	v_lshl_add_u64 v[50:51], v[120:121], 0, v[50:51]
	v_lshl_add_u64 v[54:55], v[120:121], 0, v[52:53]
	v_lshl_add_u64 v[58:59], v[120:121], 0, v[58:59]
	v_lshl_add_u64 v[62:63], v[120:121], 0, v[60:61]
	global_load_dwordx4 v[50:53], v[50:51], off
	s_nop 0
	global_load_dwordx4 v[54:57], v[54:55], off
	s_nop 0
	global_load_dwordx4 v[58:61], v[58:59], off
	s_nop 0
	global_load_dwordx4 v[62:65], v[62:63], off
	v_or_b32_e32 v66, s23, v195
	v_or_b32_e32 v68, s23, v196
	v_lshlrev_b32_e32 v66, 1, v66
	v_mov_b32_e32 v67, v119
	v_lshlrev_b32_e32 v68, 1, v68
	v_mov_b32_e32 v69, v119
	v_or_b32_e32 v74, s23, v197
	v_lshl_add_u64 v[66:67], v[120:121], 0, v[66:67]
	v_lshl_add_u64 v[70:71], v[120:121], 0, v[68:69]
	v_lshlrev_b32_e32 v74, 1, v74
	v_mov_b32_e32 v75, v119
	v_add_lshl_u32 v76, s23, v198, 1
	v_mov_b32_e32 v77, v119
	global_load_dwordx4 v[66:69], v[66:67], off
	s_nop 0
	global_load_dwordx4 v[70:73], v[70:71], off
	v_lshl_add_u64 v[74:75], v[120:121], 0, v[74:75]
	v_lshl_add_u64 v[78:79], v[120:121], 0, v[76:77]
	global_load_dwordx4 v[74:77], v[74:75], off
	s_nop 0
	global_load_dwordx4 v[78:81], v[78:79], off
	s_lshl_b32 s23, s57, 18
	v_or_b32_e32 v82, s23, v199
	v_lshlrev_b32_e32 v82, 1, v82
	v_mov_b32_e32 v83, v119
	v_lshl_add_u64 v[82:83], v[122:123], 0, v[82:83]
	global_load_dwordx4 v[178:181], v[82:83], off
	v_add_lshl_u32 v82, s23, v201, 1
	v_mov_b32_e32 v83, v119
	v_lshl_add_u64 v[82:83], v[122:123], 0, v[82:83]
	global_load_dwordx4 v[222:225], v[82:83], off
	s_lshl_b32 s23, s57, 7
	v_mov_b32_e32 v83, v119
	v_add_u32_e32 v82, s23, v186
	v_lshlrev_b64 v[82:83], 11, v[82:83]
	v_lshl_add_u64 v[110:111], v[124:125], 0, v[82:83]
	global_load_dwordx4 v[82:85], v[110:111], off
	global_load_dwordx4 v[86:89], v[110:111], off offset:64
	global_load_dwordx4 v[90:93], v[110:111], off offset:128
	global_load_dwordx4 v[94:97], v[110:111], off offset:192
	global_load_dwordx4 v[98:101], v[110:111], off offset:256

; __device__ __forceinline__ unsigned cvt_pk_bf16(float lo, float hi) { const bf16x2_cv v = __builtin_convertvector((f32x2_cv){lo, hi}, bf16x2_cv); return __builtin_bit_cast(unsigned, v); }
; #define LAS __attribute__((address_space(3)))
; __device__ __forceinline__ void retention_fused(const Params& p, LAS unsigned char* lds, int unit) {
;     ...
; #pragma unroll
;         for (int mt = 0; mt < 2; ++mt)
; #pragma unroll
;             for (int nt = 0; nt < 4; ++nt) { u32x2 w; w.x = cvt_pk_bf16(S[mt][nt][0], S[mt][nt][1]); w.y = cvt_pk_bf16(S[mt][nt][2], S[mt][nt][3]);
;                 *(LAS u32x2*)(St + (nt * 16 + fr) * ST_STRIDE + (32 * wid + 16 * mt + fq * 4) * 2) = w; }
; #pragma unroll
;         for (int i = 0; i < 8; ++i) { const int id = tid + i * NTHREADS, row = id >> 5, cc = id & 31; *(LAS u32x4*)(Ks + row * KS_STRIDE + cc * 16) = *(const u32x4*)(Kg + (size_t)(c * 128 + row) * D + cc * 8); }
; #pragma unroll
;         for (int i = 0; i < 2; ++i) { const int id = tid + i * NTHREADS, row = id >> 3, cc = id & 7;
;             const u32x4 v = *(const u32x4*)(Vg + (size_t)(c * 128 + row) * VD + cc * 8);
;             *(LAS u32x4*)(Vs + row * VS_STRIDE + cc * 16) = v;
;             const float sw = __builtin_amdgcn_exp2f((float)(127 - row) * log2g);
;             u32x4 w; w.x = cvt_pk_bf16(bflo(v.x) * sw, bfhi(v.x) * sw); w.y = cvt_pk_bf16(bflo(v.y) * sw, bfhi(v.y) * sw); w.z = cvt_pk_bf16(bflo(v.z) * sw, bfhi(v.z) * sw); w.w = cvt_pk_bf16(bflo(v.w) * sw, bfhi(v.w) * sw);
;             *(LAS u32x4*)(Vw + row * VS_STRIDE + cc * 16) = w; }
;         bf16x8 qf[8];
; #pragma unroll
;         for (int ks = 0; ks < 8; ++ks) qf[ks] = *(const bf16x8*)(Qg + (size_t)(c * 128 + 16 * wid + fr) * D + ks * 32 + fq * 8);
;         __syncthreads();
.LBB0_1046:
	s_lshl_b32 s23, s57, 7
	v_cvt_pk_bf16_f32 v102, v30, v31
	v_cvt_pk_bf16_f32 v103, v32, v33
	v_cvt_pk_bf16_f32 v112, v2, v3
	v_cvt_pk_bf16_f32 v113, v4, v5
	v_cvt_pk_bf16_f32 v104, v18, v19
	v_cvt_pk_bf16_f32 v105, v20, v21
	v_cvt_pk_bf16_f32 v106, v22, v23
	v_cvt_pk_bf16_f32 v107, v24, v25
	v_cvt_pk_bf16_f32 v226, v6, v7
	v_cvt_pk_bf16_f32 v227, v8, v9
	v_add_u32_e32 v117, 0x2000, v208
	v_cvt_pk_bf16_f32 v228, v10, v11
	v_cvt_pk_bf16_f32 v229, v12, v13
	v_add_u32_e32 v161, 0x4000, v208
	ds_write2_b64 v208, v[102:103], v[112:113] offset1:4
	ds_write2_b64 v117, v[104:105], v[226:227] offset0:32 offset1:36
	ds_write2_b64 v161, v[106:107], v[228:229] offset0:64 offset1:68
	global_load_dwordx4 v[102:105], v[110:111], off offset:320
	v_cvt_pk_bf16_f32 v108, v26, v27
	v_cvt_pk_bf16_f32 v109, v28, v29
	v_cvt_pk_bf16_f32 v230, v14, v15
	v_cvt_pk_bf16_f32 v231, v16, v17
	v_add_u32_e32 v163, 0x6000, v208
	v_lshl_or_b32 v161, s58, 5, v183
	v_lshlrev_b32_e32 v182, 9, v161
	s_mov_b32 s26, 0
	v_mov_b32_e32 v117, v204
	s_mov_b32 s27, s37
	ds_write2_b64 v163, v[108:109], v[230:231] offset0:96 offset1:100
	s_waitcnt vmcnt(15)
	ds_write_b128 v209, v[50:53]
	s_waitcnt vmcnt(14)
	ds_write_b128 v210, v[54:57]
	s_waitcnt vmcnt(13)
	ds_write_b128 v209, v[58:61] offset:16896
	s_waitcnt vmcnt(12)
	ds_write_b128 v211, v[62:65]
	global_load_dwordx4 v[106:109], v[110:111], off offset:384
	s_waitcnt vmcnt(12)
	ds_write_b128 v209, v[66:69] offset:33792
	s_waitcnt vmcnt(11)
	ds_write_b128 v212, v[70:73]
	s_waitcnt vmcnt(10)
	ds_write_b128 v209, v[74:77] offset:50688
	global_load_dwordx4 v[110:113], v[110:111], off offset:448
	v_add_u32_e32 v50, v184, v200
	s_waitcnt vmcnt(10)
	ds_write_b128 v213, v[78:81]
	v_mov_b32_e32 v163, v139
	s_waitcnt vmcnt(9)
	ds_write_b128 v50, v[178:181]
	v_lshlrev_b32_e32 v50, 16, v178
	v_and_b32_e32 v51, 0xffff0000, v178
	v_lshlrev_b32_e32 v52, 16, v179
	v_and_b32_e32 v53, 0xffff0000, v179
	v_pk_mul_f32 v[50:51], v[140:141], v[50:51]
	v_pk_mul_f32 v[52:53], v[140:141], v[52:53]
	v_cvt_pk_bf16_f32 v50, v50, v51
	v_cvt_pk_bf16_f32 v51, v52, v53
	v_lshlrev_b32_e32 v52, 16, v180
	v_and_b32_e32 v53, 0xffff0000, v180
	v_lshlrev_b32_e32 v54, 16, v181
	v_and_b32_e32 v55, 0xffff0000, v181
	v_pk_mul_f32 v[52:53], v[140:141], v[52:53]
	v_pk_mul_f32 v[54:55], v[140:141], v[54:55]
	v_cvt_pk_bf16_f32 v52, v52, v53
	v_cvt_pk_bf16_f32 v53, v54, v55
	v_add_u32_e32 v54, v185, v200
	ds_write_b128 v54, v[50:53]
	v_add_u32_e32 v50, v184, v202
	s_waitcnt vmcnt(8)
	ds_write_b128 v50, v[222:225]
	v_lshlrev_b32_e32 v50, 16, v222
	v_and_b32_e32 v51, 0xffff0000, v222
	v_lshlrev_b32_e32 v52, 16, v223
	v_and_b32_e32 v53, 0xffff0000, v223
	v_pk_mul_f32 v[50:51], v[142:143], v[50:51]
	v_pk_mul_f32 v[52:53], v[142:143], v[52:53]
	v_cvt_pk_bf16_f32 v50, v50, v51
	v_cvt_pk_bf16_f32 v51, v52, v53
	v_lshlrev_b32_e32 v52, 16, v224
	v_and_b32_e32 v53, 0xffff0000, v224
	v_lshlrev_b32_e32 v54, 16, v225
	v_and_b32_e32 v55, 0xffff0000, v225
	v_pk_mul_f32 v[52:53], v[142:143], v[52:53]
	v_pk_mul_f32 v[54:55], v[142:143], v[54:55]
	v_cvt_pk_bf16_f32 v52, v52, v53
	v_cvt_pk_bf16_f32 v53, v54, v55
	v_add_u32_e32 v54, v185, v202
	ds_write_b128 v54, v[50:53]
	s_waitcnt lgkmcnt(0)
	s_barrier
; #define LAS __attribute__((address_space(3)))
; #define SAMPLE_ISSUE(hb) do { _Pragma("unroll") for (int i = 0; i < 4; ++i) s0v[i] = __builtin_nontemporal_load((const f32x4*)(S0 + (size_t)(dbase + 4 * ((hb) * 4 + i)) * 512)); } while (0)
; __device__ __forceinline__ void retention_fused(const Params& p, LAS unsigned char* lds, int unit) {
;     ...
;         SAMPLE_ISSUE(0);
;         f32x4 o[4];
; #pragma unroll
;         for (int nt = 0; nt < 4; ++nt) {
;             o[nt] = (f32x4){0.f, 0.f, 0.f, 0.f};
; #pragma unroll
;             for (int ks = 0; ks < 8; ++ks) { const bf16x8 sf = *(const LAS bf16x8*)(St + (nt * 16 + fr) * ST_STRIDE + ks * 64 + fq * 16);
;                 o[nt] = __builtin_amdgcn_mfma_f32_16x16x32_bf16(qf[ks], sf, o[nt], 0, 0, 0); }
; #pragma unroll
;             for (int r = 0; r < 4; ++r) o[nt][r] *= __builtin_amdgcn_exp2f((float)(16 * wid + fq * 4 + r + 1) * log2g);
;         }
	ds_read_b128 v[226:229], v214
	ds_read_b128 v[230:233], v214 offset:64
	ds_read_b128 v[234:237], v214 offset:128
	ds_read_b128 v[238:241], v214 offset:192
	ds_read_b128 v[242:245], v214 offset:256
	ds_read_b128 v[248:251], v214 offset:320
	ds_read_b128 v[252:255], v214 offset:384
	v_lshlrev_b32_e32 v178, 11, v161
	v_mov_b32_e32 v179, v119
	v_lshl_add_u64 v[180:181], v[164:165], 0, v[178:179]
	global_load_dwordx4 v[78:81], v[180:181], off nt
	v_add_co_u32_e32 v70, vcc, s52, v180
	s_nop 1
	v_addc_co_u32_e32 v71, vcc, 0, v181, vcc
	global_load_dwordx4 v[74:77], v[70:71], off nt
	v_add_co_u32_e32 v66, vcc, s51, v180
	s_nop 1
	v_addc_co_u32_e32 v67, vcc, 0, v181, vcc
	v_add_co_u32_e32 v68, vcc, s53, v180
	s_nop 1
	v_addc_co_u32_e32 v69, vcc, 0, v181, vcc
	global_load_dwordx4 v[70:73], v[66:67], off nt
	s_nop 0
	global_load_dwordx4 v[66:69], v[68:69], off nt
	s_waitcnt vmcnt(11) lgkmcnt(6)
	v_mfma_f32_16x16x32_bf16 v[62:65], v[82:85], v[226:229], 0
	ds_read_b128 v[222:225], v214 offset:448
	s_waitcnt vmcnt(10) lgkmcnt(6)
	v_mfma_f32_16x16x32_bf16 v[62:65], v[86:89], v[230:233], v[62:65]
	ds_read_b128 v[226:229], v214 offset:8448
	s_waitcnt vmcnt(9) lgkmcnt(6)
	v_mfma_f32_16x16x32_bf16 v[62:65], v[90:93], v[234:237], v[62:65]
	ds_read_b128 v[230:233], v214 offset:8512
	s_waitcnt vmcnt(8) lgkmcnt(6)
	v_mfma_f32_16x16x32_bf16 v[62:65], v[94:97], v[238:241], v[62:65]
	ds_read_b128 v[234:237], v214 offset:8576
	s_waitcnt vmcnt(7) lgkmcnt(6)
	v_mfma_f32_16x16x32_bf16 v[62:65], v[98:101], v[242:245], v[62:65]
	ds_read_b128 v[238:241], v214 offset:8640
	s_waitcnt vmcnt(6) lgkmcnt(6)
	v_mfma_f32_16x16x32_bf16 v[62:65], v[102:105], v[248:251], v[62:65]
	ds_read_b128 v[242:245], v214 offset:8704
	s_waitcnt vmcnt(5) lgkmcnt(6)
	v_mfma_f32_16x16x32_bf16 v[62:65], v[106:109], v[252:255], v[62:65]
	ds_read_b128 v[248:251], v214 offset:8768
	s_waitcnt vmcnt(4) lgkmcnt(6)
	v_mfma_f32_16x16x32_bf16 v[62:65], v[110:113], v[222:225], v[62:65]
	ds_read_b128 v[252:255], v214 offset:8832
	s_waitcnt lgkmcnt(6)
	v_mfma_f32_16x16x32_bf16 v[58:61], v[82:85], v[226:229], 0
	ds_read_b128 v[222:225], v214 offset:8896
	s_waitcnt lgkmcnt(6)
	v_mfma_f32_16x16x32_bf16 v[58:61], v[86:89], v[230:233], v[58:61]
	ds_read_b128 v[226:229], v214 offset:16896
	s_waitcnt lgkmcnt(6)
	v_mfma_f32_16x16x32_bf16 v[58:61], v[90:93], v[234:237], v[58:61]
	ds_read_b128 v[230:233], v214 offset:16960
	s_waitcnt lgkmcnt(6)
	v_mfma_f32_16x16x32_bf16 v[58:61], v[94:97], v[238:241], v[58:61]
	ds_read_b128 v[234:237], v214 offset:17024
	s_waitcnt lgkmcnt(6)
	v_mfma_f32_16x16x32_bf16 v[58:61], v[98:101], v[242:245], v[58:61]
	ds_read_b128 v[238:241], v214 offset:17088
	s_waitcnt lgkmcnt(6)
	v_mfma_f32_16x16x32_bf16 v[58:61], v[102:105], v[248:251], v[58:61]
	ds_read_b128 v[242:245], v214 offset:17152
	s_waitcnt lgkmcnt(6)
	v_mfma_f32_16x16x32_bf16 v[58:61], v[106:109], v[252:255], v[58:61]
	ds_read_b128 v[248:251], v214 offset:17216
	s_waitcnt lgkmcnt(6)
	v_mfma_f32_16x16x32_bf16 v[58:61], v[110:113], v[222:225], v[58:61]
	ds_read_b128 v[252:255], v214 offset:17280
	s_waitcnt lgkmcnt(6)
	v_mfma_f32_16x16x32_bf16 v[54:57], v[82:85], v[226:229], 0
	ds_read_b128 v[222:225], v214 offset:17344
	s_waitcnt lgkmcnt(6)
	v_mfma_f32_16x16x32_bf16 v[54:57], v[86:89], v[230:233], v[54:57]
	ds_read_b128 v[226:229], v214 offset:25344
	s_waitcnt lgkmcnt(6)
	v_mfma_f32_16x16x32_bf16 v[54:57], v[90:93], v[234:237], v[54:57]
	ds_read_b128 v[230:233], v214 offset:25408
	v_pk_mul_f32 v[62:63], v[144:145], v[62:63]
	s_waitcnt lgkmcnt(6)
	v_mfma_f32_16x16x32_bf16 v[54:57], v[94:97], v[238:241], v[54:57]
	ds_read_b128 v[234:237], v214 offset:25472
	s_waitcnt lgkmcnt(6)
	v_mfma_f32_16x16x32_bf16 v[54:57], v[98:101], v[242:245], v[54:57]
	ds_read_b128 v[238:241], v214 offset:25536
	v_pk_mul_f32 v[64:65], v[148:149], v[64:65]
	s_waitcnt lgkmcnt(6)
	v_mfma_f32_16x16x32_bf16 v[54:57], v[102:105], v[248:251], v[54:57]
	ds_read_b128 v[242:245], v214 offset:25600
	s_waitcnt lgkmcnt(6)
	v_mfma_f32_16x16x32_bf16 v[54:57], v[106:109], v[252:255], v[54:57]
	ds_read_b128 v[248:251], v214 offset:25664
	s_waitcnt lgkmcnt(6)
	v_mfma_f32_16x16x32_bf16 v[54:57], v[110:113], v[222:225], v[54:57]
	ds_read_b128 v[252:255], v214 offset:25728
	s_waitcnt lgkmcnt(6)
	v_mfma_f32_16x16x32_bf16 v[50:53], v[82:85], v[226:229], 0
	ds_read_b128 v[222:225], v214 offset:25792
	s_waitcnt lgkmcnt(6)
	v_mfma_f32_16x16x32_bf16 v[50:53], v[86:89], v[230:233], v[50:53]
	s_waitcnt lgkmcnt(5)
	v_mfma_f32_16x16x32_bf16 v[50:53], v[90:93], v[234:237], v[50:53]
	v_pk_mul_f32 v[58:59], v[144:145], v[58:59]
	s_waitcnt lgkmcnt(4)
	v_mfma_f32_16x16x32_bf16 v[50:53], v[94:97], v[238:241], v[50:53]
	s_waitcnt lgkmcnt(3)
	v_mfma_f32_16x16x32_bf16 v[50:53], v[98:101], v[242:245], v[50:53]
	v_pk_mul_f32 v[60:61], v[148:149], v[60:61]
	s_waitcnt lgkmcnt(2)
	v_mfma_f32_16x16x32_bf16 v[50:53], v[102:105], v[248:251], v[50:53]
	s_waitcnt lgkmcnt(1)
	v_mfma_f32_16x16x32_bf16 v[50:53], v[106:109], v[252:255], v[50:53]
	s_waitcnt lgkmcnt(0)
	v_mfma_f32_16x16x32_bf16 v[50:53], v[110:113], v[222:225], v[50:53]
	ds_read_b128 v[248:251], v163
	ds_read_b128 v[252:255], v163 offset:64
	v_pk_mul_f32 v[54:55], v[144:145], v[54:55]
	v_pk_mul_f32 v[56:57], v[148:149], v[56:57]
	s_nop 3
	v_pk_mul_f32 v[50:51], v[144:145], v[50:51]
	v_pk_mul_f32 v[52:53], v[148:149], v[52:53]
	s_branch .LBB0_1049
